# v16 + prologue de-serialisation in diff-attention component 1: first K0/V0/K1/Q/K2 loads issued before the T5 bias table build
# baseline (speedup 1.0000x reference)
;   #define DMA_K(t,slot) glds16s(Kb+(long)(t)*KVBLK*kp,ksrc,(unsigned)__builtin_amdgcn_readfirstlane(kdst+(slot)))
;   #define DMA_V(t,slot) do{ glds16s(Vb+(long)(t)*KVBLK*vp,vsrc,(unsigned)__builtin_amdgcn_readfirstlane(vdst+(slot))); \
;       if(VH==2) glds16s(Vb+(long)(t)*KVBLK*vp+64,vsrc,(unsigned)__builtin_amdgcn_readfirstlane(vdst+(slot)+8192)); }while(0)
; template<int VH,bool HAS_BIAS,int MODE> __device__ __forceinline__ void attn_unit2(const bf16*Qb,int qp,const bf16*__restrict__ Kb,int kp,const bf16*__restrict__ Vb,int vp,bf16*Ob,int op,int q0,int NT,const float*relb,char*shm,float lam,const float*subg,float gmul){
;     ...
;   if(HAS_BIAS){ const float L2E=1.4426950408889634f; cb=L2E*relb[15*8]; ca=L2E*relb[31*8];
;     for(int i=tid;i<768;i+=512){ const int rel=i-384; const int n=rel<0?-rel:rel; int bk=n<8?n:(8+(31-__builtin_clz((unsigned)(n*n)))-6); if(n>=8&&bk>15)bk=15; if(rel>0)bk+=16; btab[i]=L2E*relb[bk*8]; } }
;     ...
;   DMA_K(0,0);DMA_V(0,0);DMA_K(1,KSL);
;   bf16x8 qr[4];
;   #pragma unroll
;   for(int d0=0;d0<4;++d0)qr[d0]=*reinterpret_cast<const bf16x8*>(&Qw[(long)r32*qp+d0*16+hi*8]);
;   DMA_K(2,2*KSL);
.LBB0_1073:
	s_lshl_b64 s[6:7], s[16:17], 2
	s_waitcnt lgkmcnt(0)
	s_add_u32 s40, s20, s6
	s_addc_u32 s41, s21, s7
	v_mov_b32_e32 v184, v182
	global_load_dword v0, v1, s[40:41] offset:480
	global_load_dword v34, v1, s[40:41] offset:992
	v_readfirstlane_b32 s56, v184
	s_lshl_b64 s[98:99], s[22:23], 1
	s_lshl_b32 s8, s16, 8
	s_add_u32 s100, s36, s98
	s_addc_u32 s101, s37, s99
	s_add_u32 s100, s100, s8
	s_addc_u32 s101, s101, 0
	s_ashr_i32 s9, s56, 6
	s_lshl_b32 s7, s9, 4
	v_and_b32_e32 v253, 63, v184
	v_lshl_add_u32 v202, v253, 11, s7
	s_lshl_b32 s6, s9, 10
	s_mov_b32 m0, s6
	s_nop 0
	global_load_lds_dwordx4 v202, s[100:101]
	v_bfe_u32 v253, v184, 2, 4
	v_and_or_b32 v253, s7, 48, v253
	s_ashr_i32 s10, s56, 3
	s_and_b32 s10, s10, 0x7fffffe0
	v_lshl_add_u32 v253, v253, 10, s10
	v_lshlrev_b32_e32 v254, 3, v184
	v_and_b32_e32 v254, 24, v254
	v_or_b32_e32 v253, v253, v254
	v_lshlrev_b32_e32 v203, 1, v253
	s_add_u32 s10, s38, s98
	s_addc_u32 s11, s39, s99
	s_add_u32 s10, s10, s8
	s_addc_u32 s11, s11, 0
	s_add_i32 m0, s6, 0x8000
	s_nop 0
	global_load_lds_dwordx4 v203, s[10:11]
	s_add_u32 s10, s10, 0x80
	s_addc_u32 s11, s11, 0
	s_add_i32 m0, s6, 0xa000
	s_nop 0
	global_load_lds_dwordx4 v203, s[10:11]
	s_add_u32 s100, s100, 0x20000
	s_addc_u32 s101, s101, 0
	s_add_i32 m0, s6, 0x2000
	s_nop 0
	global_load_lds_dwordx4 v202, s[100:101]
	s_add_u32 s10, s28, s98
	s_addc_u32 s11, s29, s99
	s_add_u32 s10, s10, s8
	s_addc_u32 s11, s11, 0
	s_lshl_b32 s7, s54, 8
	s_lshl_b32 s8, s9, 5
	s_add_i32 s8, s8, s7
	s_ashr_i32 s9, s8, 31
	s_lshl_b64 s[8:9], s[8:9], 11
	s_add_u32 s10, s10, s8
	s_addc_u32 s11, s11, s9
	v_and_b32_e32 v253, 31, v184
	v_bfe_u32 v254, v184, 5, 1
	v_lshlrev_b32_e32 v253, 11, v253
	v_lshl_or_b32 v253, v254, 4, v253
	global_load_dwordx4 v[158:161], v253, s[10:11]
	global_load_dwordx4 v[154:157], v253, s[10:11] offset:32
	global_load_dwordx4 v[150:153], v253, s[10:11] offset:64
	global_load_dwordx4 v[146:149], v253, s[10:11] offset:96
	s_add_u32 s100, s100, 0x20000
	s_addc_u32 s101, s101, 0
	s_add_i32 m0, s6, 0x4000
	s_nop 0
	global_load_lds_dwordx4 v202, s[100:101]
	v_cmp_gt_i32_e32 vcc, s64, v184
	s_and_saveexec_b64 s[42:43], vcc
	s_cbranch_execz .LBB0_1085
	v_max_i32_e32 v2, 0x100, v184
	v_sub_u32_e32 v2, v2, v184
	v_add_u32_e32 v3, 0x1ff, v2
	v_cmp_lt_u32_e32 vcc, s63, v3
	s_mov_b64 s[6:7], -1
	v_mov_b32_e32 v2, v184
	s_and_saveexec_b64 s[44:45], vcc
	s_cbranch_execz .LBB0_1082
	v_lshrrev_b32_e32 v4, 9, v3
	v_add_u32_e32 v185, 0x200, v184
	v_add_u32_e32 v5, -1, v4
	v_cmp_lt_u32_e32 vcc, 1, v5
	v_mov_b32_e32 v6, 0
	v_mov_b64_e32 v[2:3], v[184:185]
	s_and_saveexec_b64 s[46:47], vcc
	s_cbranch_execz .LBB0_1079
	v_lshrrev_b32_e32 v2, 1, v5
	v_add_u32_e32 v2, 1, v2
	v_and_b32_e32 v6, -2, v2
	v_lshl_add_u32 v7, v184, 2, s65
	s_mov_b32 s33, 0
	s_mov_b64 s[48:49], 0
	v_mov_b64_e32 v[2:3], v[184:185]

; #define WAIT_BAR(N) asm volatile("s_waitcnt vmcnt(" #N ") lgkmcnt(0)\n\ts_barrier":::"memory")
;   #define DMA_K(t,slot) glds16s(Kb+(long)(t)*KVBLK*kp,ksrc,(unsigned)__builtin_amdgcn_readfirstlane(kdst+(slot)))
;   #define DMA_V(t,slot) do{ glds16s(Vb+(long)(t)*KVBLK*vp,vsrc,(unsigned)__builtin_amdgcn_readfirstlane(vdst+(slot))); \
;       if(VH==2) glds16s(Vb+(long)(t)*KVBLK*vp+64,vsrc,(unsigned)__builtin_amdgcn_readfirstlane(vdst+(slot)+8192)); }while(0)
; template<int VH,bool HAS_BIAS,int MODE> __device__ __forceinline__ void attn_unit2(const bf16*Qb,int qp,const bf16*__restrict__ Kb,int kp,const bf16*__restrict__ Vb,int vp,bf16*Ob,int op,int q0,int NT,const float*relb,char*shm,float lam,const float*subg,float gmul){
;     ...
;   DMA_K(0,0);DMA_V(0,0);DMA_K(1,KSL);
;   bf16x8 qr[4];
;   #pragma unroll
;   for(int d0=0;d0<4;++d0)qr[d0]=*reinterpret_cast<const bf16x8*>(&Qw[(long)r32*qp+d0*16+hi*8]);
;   DMA_K(2,2*KSL);
;     ...
;   if(VH==1){WAIT_BAR(3);}else{WAIT_BAR(4);}
;   qkt(pA0,pA1,shm+LM::L_K,qr,zero16,r32,hi);
.LBB0_1085:
	s_or_b64 exec, exec, s[42:43]
	s_lshl_b64 s[22:23], s[22:23], 1
	s_add_u32 s6, s28, s22
	s_addc_u32 s7, s29, s23
	s_lshl_b32 s68, s16, 7
	s_lshl_b32 s8, s16, 8
	s_add_u32 s75, s6, s8
	s_addc_u32 s76, s7, 0
	s_add_u32 s6, s36, s22
	s_addc_u32 s7, s37, s23
	s_add_u32 s44, s6, s8
	s_addc_u32 s45, s7, 0
	s_add_u32 s6, s38, s22
	s_addc_u32 s7, s39, s23
	s_add_u32 s46, s6, s8
	s_addc_u32 s47, s7, 0
	s_ashr_i32 s8, s56, 6
	s_lshl_b32 s77, s54, 8
	s_lshl_b32 s6, s8, 5
	s_add_i32 s6, s6, s77
	s_ashr_i32 s7, s6, 31
	s_lshl_b64 s[10:11], s[6:7], 11
	s_add_u32 s10, s75, s10
	v_and_b32_e32 v193, 63, v184
	s_addc_u32 s11, s76, s11
	s_lshl_b32 s7, s8, 4
	v_bfe_u32 v2, v184, 2, 4
	v_lshl_add_u32 v202, v193, 11, s7
	v_and_or_b32 v2, s7, 48, v2
	s_ashr_i32 s7, s56, 3
	s_and_b32 s7, s7, 0x7fffffe0
	v_lshl_add_u32 v2, v2, 10, s7
	s_lshl_b32 s7, s8, 10
	s_cmp_lg_u32 0, -1
	s_cselect_b32 s9, 0, 0
	s_add_i32 s33, s7, s9
	s_add_i32 s9, s6, 0xffffffa6
	s_add_i32 s59, s33, 0x8000
	s_ashr_i32 s9, s9, 6
	v_lshlrev_b32_e32 v3, 3, v184
	s_cmpk_gt_i32 s6, 0x59
	v_and_b32_e32 v195, 24, v3
	s_cselect_b32 s57, s9, 0
	s_add_i32 s9, s6, 0xb9
	v_or_b32_e32 v2, v2, v195
	s_ashr_i32 s58, s9, 6
	v_lshlrev_b32_e32 v203, 1, v2
	s_add_u32 s48, s46, 0x80
	v_and_b32_e32 v185, 31, v184
	s_addc_u32 s49, s47, 0
	s_add_i32 s9, s33, 0xa000
	v_bfe_u32 v35, v184, 5, 1
	s_add_u32 s42, s44, 0x20000
	v_lshlrev_b32_e32 v2, 11, v185
	s_addc_u32 s43, s45, 0
	s_add_i32 s9, s33, 0x2000
	v_lshl_or_b32 v2, v35, 4, v2
	s_add_u32 s10, s44, 0x40000
	v_lshlrev_b32_e32 v2, 10, v35
	v_lshlrev_b32_e32 v3, 4, v185
	s_addc_u32 s11, s45, 0
	s_add_i32 s9, s33, 0x4000
	v_add3_u32 v201, 0, v2, v3
	s_waitcnt vmcnt(4) lgkmcnt(0)
	s_barrier
	ds_read_b128 v[2:5], v201
	ds_read_b128 v[18:21], v201 offset:512
	ds_read_b128 v[36:39], v201 offset:2048
	s_cmp_lt_i32 s57, 1
	s_cselect_b64 s[10:11], -1, 0
	s_cmp_gt_i32 s58, 0
	s_cselect_b64 s[42:43], -1, 0
	s_and_b64 s[10:11], s[10:11], s[42:43]
	v_lshlrev_b32_e32 v194, 2, v35
	v_or_b32_e32 v200, s6, v185
	s_and_b64 vcc, exec, s[10:11]
	s_waitcnt vmcnt(3) lgkmcnt(2)
	v_mfma_f32_32x32x16_bf16 v[2:17], v[2:5], v[158:161], 0
	s_waitcnt vmcnt(2) lgkmcnt(0)
	v_mfma_f32_32x32x16_bf16 v[2:17], v[36:39], v[154:157], v[2:17]
	ds_read_b128 v[36:39], v201 offset:2560
	v_mfma_f32_32x32x16_bf16 v[18:33], v[18:21], v[158:161], 0
	s_waitcnt lgkmcnt(0)
	v_mfma_f32_32x32x16_bf16 v[18:33], v[36:39], v[154:157], v[18:33]
	ds_read_b128 v[36:39], v201 offset:4096
	s_waitcnt vmcnt(1) lgkmcnt(0)
	v_mfma_f32_32x32x16_bf16 v[2:17], v[36:39], v[150:153], v[2:17]
	ds_read_b128 v[36:39], v201 offset:4608
	s_waitcnt lgkmcnt(0)
	v_mfma_f32_32x32x16_bf16 v[18:33], v[36:39], v[150:153], v[18:33]
	ds_read_b128 v[36:39], v201 offset:6144
	s_waitcnt vmcnt(0) lgkmcnt(0)
	v_mfma_f32_32x32x16_bf16 v[2:17], v[36:39], v[146:149], v[2:17]
	ds_read_b128 v[36:39], v201 offset:6656
	s_waitcnt lgkmcnt(0)
	v_mfma_f32_32x32x16_bf16 v[18:33], v[36:39], v[146:149], v[18:33]
	s_cbranch_vccz .LBB0_1087
	v_or_b32_e32 v36, 0x180, v194
	v_sub_u32_e32 v36, v36, v200
	v_lshl_add_u32 v36, v36, 2, 0
	v_add_u32_e32 v60, 0x14800, v36
	ds_read2_b32 v[36:37], v60 offset1:1
	ds_read2_b32 v[38:39], v60 offset0:2 offset1:3
	ds_read2_b32 v[40:41], v60 offset0:8 offset1:9
	ds_read2_b32 v[42:43], v60 offset0:10 offset1:11
	ds_read2_b32 v[44:45], v60 offset0:16 offset1:17
	ds_read2_b32 v[46:47], v60 offset0:18 offset1:19
	ds_read2_b32 v[48:49], v60 offset0:24 offset1:25
	ds_read2_b32 v[50:51], v60 offset0:26 offset1:27
	ds_read2_b32 v[52:53], v60 offset0:32 offset1:33
	ds_read2_b32 v[54:55], v60 offset0:34 offset1:35
	ds_read2_b32 v[56:57], v60 offset0:40 offset1:41
	ds_read2_b32 v[58:59], v60 offset0:42 offset1:43
	s_waitcnt lgkmcnt(4)
	v_pk_add_f32 v[16:17], v[16:17], v[50:51]
	v_pk_add_f32 v[14:15], v[14:15], v[48:49]
	v_pk_add_f32 v[12:13], v[12:13], v[46:47]
	v_pk_add_f32 v[10:11], v[10:11], v[44:45]
	ds_read2_b32 v[44:45], v60 offset0:48 offset1:49
	ds_read2_b32 v[46:47], v60 offset0:50 offset1:51
	ds_read2_b32 v[48:49], v60 offset0:56 offset1:57
	ds_read2_b32 v[50:51], v60 offset0:58 offset1:59
	v_pk_add_f32 v[8:9], v[8:9], v[42:43]
	v_pk_add_f32 v[6:7], v[6:7], v[40:41]
	v_pk_add_f32 v[4:5], v[4:5], v[38:39]
	v_pk_add_f32 v[2:3], v[2:3], v[36:37]
	s_waitcnt lgkmcnt(0)
	v_pk_add_f32 v[32:33], v[32:33], v[50:51]
	v_pk_add_f32 v[30:31], v[30:31], v[48:49]
	v_pk_add_f32 v[28:29], v[28:29], v[46:47]
	v_pk_add_f32 v[26:27], v[26:27], v[44:45]
	v_pk_add_f32 v[24:25], v[24:25], v[58:59]
	v_pk_add_f32 v[22:23], v[22:23], v[56:57]
	v_pk_add_f32 v[20:21], v[20:21], v[54:55]
	v_pk_add_f32 v[18:19], v[18:19], v[52:53]

; __global__ void __launch_bounds__(NWAVES * 64, 2) mega_fwd(Args args) {
	.amdhsa_kernel _Z8mega_fwd4Args
		.amdhsa_group_segment_fixed_size 0
		.amdhsa_private_segment_fixed_size 0
		.amdhsa_kernarg_size 464
		.amdhsa_user_sgpr_count 2
		.amdhsa_user_sgpr_dispatch_ptr 0
		.amdhsa_user_sgpr_queue_ptr 0
		.amdhsa_user_sgpr_kernarg_segment_ptr 1
		.amdhsa_user_sgpr_dispatch_id 0
		.amdhsa_user_sgpr_kernarg_preload_length 0
		.amdhsa_user_sgpr_kernarg_preload_offset 0
		.amdhsa_user_sgpr_private_segment_size 0
		.amdhsa_uses_dynamic_stack 0
		.amdhsa_enable_private_segment 0
		.amdhsa_system_sgpr_workgroup_id_x 1
		.amdhsa_system_sgpr_workgroup_id_y 0
		.amdhsa_system_sgpr_workgroup_id_z 0
		.amdhsa_system_sgpr_workgroup_info 0
		.amdhsa_system_vgpr_workitem_id 2
		.amdhsa_next_free_vgpr 256
		.amdhsa_next_free_sgpr 102
		.amdhsa_accum_offset 256
		.amdhsa_reserve_vcc 1
		.amdhsa_float_round_mode_32 0
		.amdhsa_float_round_mode_16_64 0
		.amdhsa_float_denorm_mode_32 3
		.amdhsa_float_denorm_mode_16_64 3
		.amdhsa_dx10_clamp 1
		.amdhsa_ieee_mode 1
		.amdhsa_fp16_overflow 0
		.amdhsa_tg_split 0
		.amdhsa_exception_fp_ieee_invalid_op 0
		.amdhsa_exception_fp_denorm_src 0
		.amdhsa_exception_fp_ieee_div_zero 0
		.amdhsa_exception_fp_ieee_overflow 0
		.amdhsa_exception_fp_ieee_underflow 0
		.amdhsa_exception_fp_ieee_inexact 0
		.amdhsa_exception_int_div_zero 0
	.end_amdhsa_kernel

; __global__ void __launch_bounds__(NWAVES * 64, 2) mega_fwd(Args args) {
.Lfunc_end0:
	.size	_Z8mega_fwd4Args, .Lfunc_end0-_Z8mega_fwd4Args
	.set _Z8mega_fwd4Args.num_vgpr, 256
	.set _Z8mega_fwd4Args.num_agpr, 0
	.set _Z8mega_fwd4Args.numbered_sgpr, 102
	.set _Z8mega_fwd4Args.num_named_barrier, 0
	.set _Z8mega_fwd4Args.private_seg_size, 0
	.set _Z8mega_fwd4Args.uses_vcc, 1
	.set _Z8mega_fwd4Args.uses_flat_scratch, 0
	.set _Z8mega_fwd4Args.has_dyn_sized_stack, 0
	.set _Z8mega_fwd4Args.has_recursion, 0
	.set _Z8mega_fwd4Args.has_indirect_call, 0

; __global__ void __launch_bounds__(NWAVES * 64, 2) mega_fwd(Args args) {
amdhsa.kernels:
  - .agpr_count:     0
    .args:
      - .offset:         0
        .size:           208
        .value_kind:     by_value
      - .offset:         208
        .size:           4
        .value_kind:     hidden_block_count_x
      - .offset:         212
        .size:           4
        .value_kind:     hidden_block_count_y
      - .offset:         216
        .size:           4
        .value_kind:     hidden_block_count_z
      - .offset:         220
        .size:           2
        .value_kind:     hidden_group_size_x
      - .offset:         222
        .size:           2
        .value_kind:     hidden_group_size_y
      - .offset:         224
        .size:           2
        .value_kind:     hidden_group_size_z
      - .offset:         226
        .size:           2
        .value_kind:     hidden_remainder_x
      - .offset:         228
        .size:           2
        .value_kind:     hidden_remainder_y
      - .offset:         230
        .size:           2
        .value_kind:     hidden_remainder_z
      - .offset:         248
        .size:           8
        .value_kind:     hidden_global_offset_x
      - .offset:         256
        .size:           8
        .value_kind:     hidden_global_offset_y
      - .offset:         264
        .size:           8
        .value_kind:     hidden_global_offset_z
      - .offset:         272
        .size:           2
        .value_kind:     hidden_grid_dims
      - .offset:         296
        .size:           8
        .value_kind:     hidden_multigrid_sync_arg
      - .offset:         328
        .size:           4
        .value_kind:     hidden_dynamic_lds_size
    .group_segment_fixed_size: 0
    .kernarg_segment_align: 8
    .kernarg_segment_size: 464
    .language:       OpenCL C
    .language_version:
      - 2
      - 0
    .max_flat_workgroup_size: 512
    .name:           _Z8mega_fwd4Args
    .private_segment_fixed_size: 0
    .sgpr_count:     108
    .sgpr_spill_count: 5
    .symbol:         _Z8mega_fwd4Args.kd
    .uniform_work_group_size: 1
    .uses_dynamic_stack: false
    .vgpr_count:     256
    .vgpr_spill_count: 0
    .wavefront_size: 64
